# GEMM epilogues (gate|up, out-proj, down): lane transposition of group k lands in its own registers, group k stored after group k+1 is issued (no wait for the LDS round trip)
# baseline (speedup 1.0000x reference)
; __device__ __forceinline__ unsigned cvt_pk_bf16(float lo, float hi) { unsigned r; asm volatile("v_cvt_pk_bf16_f32 %0, %1, %2" : "=v"(r) : "v"(lo), "v"(hi)); return r; }
;     __device__ __forceinline__ void operator()(const f32x4 (&acc)[2][2][4][2], const Unit& u, int wr, int wc, int fr, int fq) const {
;     ...
;         for (int ai = 0; ai < 2; ++ai)
; #pragma unroll
;             for (int m = 0; m < 4; ++m) { bf16_t* rowp = base + (size_t)(row0 + ai * HALF + m * 16) * ldc + col0;
; #pragma unroll
;                 for (int bj = 0; bj < 2; ++bj) { f32x4 v0 = acc[ai][bj][m][0] + bv[bj][0], v1 = acc[ai][bj][m][1] + bv[bj][1];
;                     if (ACT == 1) { f32x2 a = gelu_pk((f32x2){v0[0], v0[1]}), b = gelu_pk((f32x2){v0[2], v0[3]}), c = gelu_pk((f32x2){v1[0], v1[1]}), d = gelu_pk((f32x2){v1[2], v1[3]});
;                         v0 = (f32x4){a.x, a.y, b.x, b.y}; v1 = (f32x4){c.x, c.y, d.x, d.y}; }
;                     v0 = v0 * sc; v1 = v1 * sc; u32x4 w; w.x = cvt_pk_bf16(v0[0], v0[1]); w.y = cvt_pk_bf16(v0[2], v0[3]); w.z = cvt_pk_bf16(v1[0], v1[1]); w.w = cvt_pk_bf16(v1[2], v1[3]);
;                     *(u32x4*)(rowp + bj * HALF) = w; } }
.LBB0_446:
	v_lshl_add_u32 v146, s64, 8, v142
	v_lshl_or_b32 v140, s63, 8, v144
	v_ashrrev_i32_e32 v141, 31, v140
	v_ashrrev_i32_e32 v147, 31, v146
	v_lshl_add_u64 v[148:149], v[140:141], 1, s[82:83]
	v_lshlrev_b64 v[140:141], 11, v[146:147]
	v_lshl_add_u64 v[140:141], v[148:149], 0, v[140:141]
	v_pk_add_f32 v[128:129], v[128:129], 0 op_sel_hi:[1,0]
	v_pk_add_f32 v[126:127], v[126:127], 0 op_sel_hi:[1,0]
	v_pk_add_f32 v[150:151], v[124:125], 0 op_sel_hi:[1,0]
	v_pk_add_f32 v[124:125], v[122:123], 0 op_sel_hi:[1,0]
	v_cvt_pk_bf16_f32 v122, v126, v127
	v_cvt_pk_bf16_f32 v123, v128, v129
	v_pk_add_f32 v[118:119], v[118:119], 0 op_sel_hi:[1,0]
	v_cvt_pk_bf16_f32 v124, v124, v125
	v_cvt_pk_bf16_f32 v125, v150, v151
	ds_bpermute_b32 v208, v248, v122
	ds_bpermute_b32 v209, v248, v123
	ds_bpermute_b32 v210, v248, v124
	ds_bpermute_b32 v211, v248, v125
	v_mov_b32_e32 v224, v140
	v_mov_b32_e32 v225, v141
	v_pk_add_f32 v[120:121], v[120:121], 0 op_sel_hi:[1,0]
	v_pk_add_f32 v[114:115], v[114:115], 0 op_sel_hi:[1,0]
	v_pk_add_f32 v[122:123], v[112:113], 0 op_sel_hi:[1,0]
	v_pk_add_f32 v[112:113], v[110:111], 0 op_sel_hi:[1,0]
	v_cvt_pk_bf16_f32 v110, v118, v119
	v_cvt_pk_bf16_f32 v111, v120, v121
	v_pk_add_f32 v[102:103], v[102:103], 0 op_sel_hi:[1,0]
	v_cvt_pk_bf16_f32 v112, v112, v113
	v_cvt_pk_bf16_f32 v113, v122, v123
	ds_bpermute_b32 v212, v248, v110
	ds_bpermute_b32 v213, v248, v111
	ds_bpermute_b32 v214, v248, v112
	ds_bpermute_b32 v215, v248, v113
	v_mov_b32_e32 v226, v140
	v_mov_b32_e32 v227, v141
	s_waitcnt lgkmcnt(4)
	global_store_dwordx4 v[224:225], v[208:211], off
	v_pk_add_f32 v[104:105], v[104:105], 0 op_sel_hi:[1,0]
	v_pk_add_f32 v[98:99], v[98:99], 0 op_sel_hi:[1,0]
	v_or_b32_e32 v110, 16, v146
	v_ashrrev_i32_e32 v111, 31, v110
	v_lshlrev_b64 v[110:111], 11, v[110:111]
	v_lshl_add_u64 v[110:111], v[148:149], 0, v[110:111]
	v_pk_add_f32 v[112:113], v[116:117], 0 op_sel_hi:[1,0]
	v_pk_add_f32 v[116:117], v[108:109], 0 op_sel_hi:[1,0]
	v_pk_add_f32 v[108:109], v[106:107], 0 op_sel_hi:[1,0]
	v_cvt_pk_bf16_f32 v106, v114, v115
	v_cvt_pk_bf16_f32 v107, v112, v113
	v_pk_add_f32 v[86:87], v[86:87], 0 op_sel_hi:[1,0]
	v_cvt_pk_bf16_f32 v108, v108, v109
	v_cvt_pk_bf16_f32 v109, v116, v117
	ds_bpermute_b32 v216, v248, v106
	ds_bpermute_b32 v217, v248, v107
	ds_bpermute_b32 v218, v248, v108
	ds_bpermute_b32 v219, v248, v109
	v_mov_b32_e32 v228, v110
	v_mov_b32_e32 v229, v111
	s_waitcnt lgkmcnt(4)
	global_store_dwordx4 v[226:227], v[212:215], off offset:256
	v_pk_add_f32 v[88:89], v[88:89], 0 op_sel_hi:[1,0]
	v_pk_add_f32 v[82:83], v[82:83], 0 op_sel_hi:[1,0]
	v_pk_add_f32 v[106:107], v[96:97], 0 op_sel_hi:[1,0]
	v_pk_add_f32 v[96:97], v[94:95], 0 op_sel_hi:[1,0]
	v_cvt_pk_bf16_f32 v94, v102, v103
	v_cvt_pk_bf16_f32 v95, v104, v105
	v_pk_add_f32 v[72:73], v[72:73], 0 op_sel_hi:[1,0]
	v_cvt_pk_bf16_f32 v96, v96, v97
	v_cvt_pk_bf16_f32 v97, v106, v107
	ds_bpermute_b32 v220, v248, v94
	ds_bpermute_b32 v221, v248, v95
	ds_bpermute_b32 v222, v248, v96
	ds_bpermute_b32 v223, v248, v97
	v_mov_b32_e32 v230, v110
	v_mov_b32_e32 v231, v111
	s_waitcnt lgkmcnt(4)
	global_store_dwordx4 v[228:229], v[216:219], off
	v_pk_add_f32 v[70:71], v[70:71], 0 op_sel_hi:[1,0]
	s_mov_b64 s[16:17], 0x40000
	v_or_b32_e32 v94, 32, v146
	v_ashrrev_i32_e32 v95, 31, v94
	v_lshlrev_b64 v[94:95], 11, v[94:95]
	v_lshl_add_u64 v[94:95], v[148:149], 0, v[94:95]
	v_pk_add_f32 v[96:97], v[100:101], 0 op_sel_hi:[1,0]
	v_pk_add_f32 v[100:101], v[92:93], 0 op_sel_hi:[1,0]
	v_pk_add_f32 v[92:93], v[90:91], 0 op_sel_hi:[1,0]
	v_cvt_pk_bf16_f32 v90, v98, v99
	v_cvt_pk_bf16_f32 v91, v96, v97
	v_pk_add_f32 v[62:63], v[62:63], 0 op_sel_hi:[1,0]
	v_cvt_pk_bf16_f32 v92, v92, v93
	v_cvt_pk_bf16_f32 v93, v100, v101
	ds_bpermute_b32 v208, v248, v90
	ds_bpermute_b32 v209, v248, v91
	ds_bpermute_b32 v210, v248, v92
	ds_bpermute_b32 v211, v248, v93
	v_mov_b32_e32 v224, v94
	v_mov_b32_e32 v225, v95
	s_waitcnt lgkmcnt(4)
	global_store_dwordx4 v[230:231], v[220:223], off offset:256
	v_pk_add_f32 v[64:65], v[64:65], 0 op_sel_hi:[1,0]
	v_pk_add_f32 v[56:57], v[56:57], 0 op_sel_hi:[1,0]
	v_pk_add_f32 v[90:91], v[80:81], 0 op_sel_hi:[1,0]
	v_pk_add_f32 v[80:81], v[78:79], 0 op_sel_hi:[1,0]
	v_cvt_pk_bf16_f32 v78, v86, v87
	v_cvt_pk_bf16_f32 v79, v88, v89
	v_pk_add_f32 v[54:55], v[54:55], 0 op_sel_hi:[1,0]
	v_cvt_pk_bf16_f32 v80, v80, v81
	v_cvt_pk_bf16_f32 v81, v90, v91
	ds_bpermute_b32 v212, v248, v78
	ds_bpermute_b32 v213, v248, v79
	ds_bpermute_b32 v214, v248, v80
	ds_bpermute_b32 v215, v248, v81
	v_mov_b32_e32 v226, v94
	v_mov_b32_e32 v227, v95
	s_waitcnt lgkmcnt(4)
	global_store_dwordx4 v[224:225], v[208:211], off
	v_pk_add_f32 v[50:51], v[50:51], 0 op_sel_hi:[1,0]
	v_pk_add_f32 v[40:41], v[40:41], 0 op_sel_hi:[1,0]
	v_or_b32_e32 v78, 48, v146
	v_ashrrev_i32_e32 v79, 31, v78
	v_lshlrev_b64 v[78:79], 11, v[78:79]
	v_lshl_add_u64 v[78:79], v[148:149], 0, v[78:79]
	v_pk_add_f32 v[80:81], v[84:85], 0 op_sel_hi:[1,0]
	v_pk_add_f32 v[84:85], v[76:77], 0 op_sel_hi:[1,0]
	v_pk_add_f32 v[76:77], v[74:75], 0 op_sel_hi:[1,0]
	v_cvt_pk_bf16_f32 v74, v82, v83
	v_cvt_pk_bf16_f32 v75, v80, v81
	v_pk_add_f32 v[38:39], v[38:39], 0 op_sel_hi:[1,0]
	v_cvt_pk_bf16_f32 v76, v76, v77
	v_cvt_pk_bf16_f32 v77, v84, v85
	ds_bpermute_b32 v216, v248, v74
	ds_bpermute_b32 v217, v248, v75
	ds_bpermute_b32 v218, v248, v76
	ds_bpermute_b32 v219, v248, v77
	v_mov_b32_e32 v228, v78
	v_mov_b32_e32 v229, v79
	s_waitcnt lgkmcnt(4)
; __device__ __forceinline__ unsigned cvt_pk_bf16(float lo, float hi) { unsigned r; asm volatile("v_cvt_pk_bf16_f32 %0, %1, %2" : "=v"(r) : "v"(lo), "v"(hi)); return r; }
;     __device__ __forceinline__ void operator()(const f32x4 (&acc)[2][2][4][2], const Unit& u, int wr, int wc, int fr, int fq) const {
;     ...
;         for (int ai = 0; ai < 2; ++ai)
; #pragma unroll
;             for (int m = 0; m < 4; ++m) { bf16_t* rowp = base + (size_t)(row0 + ai * HALF + m * 16) * ldc + col0;
; #pragma unroll
;                 for (int bj = 0; bj < 2; ++bj) { f32x4 v0 = acc[ai][bj][m][0] + bv[bj][0], v1 = acc[ai][bj][m][1] + bv[bj][1];
;                     if (ACT == 1) { f32x2 a = gelu_pk((f32x2){v0[0], v0[1]}), b = gelu_pk((f32x2){v0[2], v0[3]}), c = gelu_pk((f32x2){v1[0], v1[1]}), d = gelu_pk((f32x2){v1[2], v1[3]});
;                         v0 = (f32x4){a.x, a.y, b.x, b.y}; v1 = (f32x4){c.x, c.y, d.x, d.y}; }
;                     v0 = v0 * sc; v1 = v1 * sc; u32x4 w; w.x = cvt_pk_bf16(v0[0], v0[1]); w.y = cvt_pk_bf16(v0[2], v0[3]); w.z = cvt_pk_bf16(v1[0], v1[1]); w.w = cvt_pk_bf16(v1[2], v1[3]);
;                     *(u32x4*)(rowp + bj * HALF) = w; } }
;     ...
;         if constexpr (!Epi::AFTER_DRAIN) { E(acc, cur, wr, wc, fr, fq); S.done(cur); }
;         if (!has_next) break;
	global_store_dwordx4 v[226:227], v[212:215], off offset:256
	v_pk_add_f32 v[34:35], v[34:35], 0 op_sel_hi:[1,0]
	v_pk_add_f32 v[24:25], v[24:25], 0 op_sel_hi:[1,0]
	v_pk_add_f32 v[74:75], v[68:69], 0 op_sel_hi:[1,0]
	v_pk_add_f32 v[68:69], v[66:67], 0 op_sel_hi:[1,0]
	v_cvt_pk_bf16_f32 v66, v70, v71
	v_cvt_pk_bf16_f32 v67, v72, v73
	v_pk_add_f32 v[22:23], v[22:23], 0 op_sel_hi:[1,0]
	v_cvt_pk_bf16_f32 v68, v68, v69
	v_cvt_pk_bf16_f32 v69, v74, v75
	ds_bpermute_b32 v220, v248, v66
	ds_bpermute_b32 v221, v248, v67
	ds_bpermute_b32 v222, v248, v68
	ds_bpermute_b32 v223, v248, v69
	v_mov_b32_e32 v230, v78
	v_mov_b32_e32 v231, v79
	s_waitcnt lgkmcnt(4)
	global_store_dwordx4 v[228:229], v[216:219], off
	v_pk_add_f32 v[18:19], v[18:19], 0 op_sel_hi:[1,0]
	v_pk_add_f32 v[8:9], v[8:9], 0 op_sel_hi:[1,0]
	v_lshl_add_u64 v[66:67], v[140:141], 0, s[16:17]
	s_mov_b32 s16, 0x40000
	v_pk_add_f32 v[68:69], v[60:61], 0 op_sel_hi:[1,0]
	v_pk_add_f32 v[60:61], v[58:59], 0 op_sel_hi:[1,0]
	v_cvt_pk_bf16_f32 v58, v62, v63
	v_add_co_u32_e32 v62, vcc, s16, v140
	v_cvt_pk_bf16_f32 v59, v64, v65
	v_cvt_pk_bf16_f32 v60, v60, v61
	v_cvt_pk_bf16_f32 v61, v68, v69
	s_mov_b64 s[16:17], 0x48000
	s_nop 0
	v_addc_co_u32_e32 v63, vcc, 0, v141, vcc
	ds_bpermute_b32 v208, v248, v58
	ds_bpermute_b32 v209, v248, v59
	ds_bpermute_b32 v210, v248, v60
	ds_bpermute_b32 v211, v248, v61
	v_mov_b32_e32 v224, v62
	v_mov_b32_e32 v225, v63
	s_waitcnt lgkmcnt(4)
	global_store_dwordx4 v[230:231], v[220:223], off offset:256
	v_pk_add_f32 v[6:7], v[6:7], 0 op_sel_hi:[1,0]
	s_nop 0
	v_pk_add_f32 v[58:59], v[48:49], 0 op_sel_hi:[1,0]
	v_pk_add_f32 v[48:49], v[46:47], 0 op_sel_hi:[1,0]
	v_cvt_pk_bf16_f32 v46, v54, v55
	v_cvt_pk_bf16_f32 v47, v56, v57
	s_nop 0
	v_cvt_pk_bf16_f32 v48, v48, v49
	v_cvt_pk_bf16_f32 v49, v58, v59
	ds_bpermute_b32 v212, v248, v46
	ds_bpermute_b32 v213, v248, v47
	ds_bpermute_b32 v214, v248, v48
	ds_bpermute_b32 v215, v248, v49
	v_mov_b32_e32 v226, v66
	v_mov_b32_e32 v227, v67
	s_waitcnt lgkmcnt(4)
	global_store_dwordx4 v[224:225], v[208:211], off
	s_nop 1
	v_lshl_add_u64 v[46:47], v[140:141], 0, s[16:17]
	v_pk_add_f32 v[48:49], v[52:53], 0 op_sel_hi:[1,0]
	s_mov_b32 s16, 0x48000
	v_pk_add_f32 v[52:53], v[44:45], 0 op_sel_hi:[1,0]
	v_pk_add_f32 v[44:45], v[42:43], 0 op_sel_hi:[1,0]
	v_cvt_pk_bf16_f32 v42, v50, v51
	v_cvt_pk_bf16_f32 v43, v48, v49
	v_add_co_u32_e32 v48, vcc, s16, v140
	v_cvt_pk_bf16_f32 v44, v44, v45
	v_cvt_pk_bf16_f32 v45, v52, v53
	s_mov_b64 s[16:17], 0x50000
	s_nop 0
	v_addc_co_u32_e32 v49, vcc, 0, v141, vcc
	ds_bpermute_b32 v216, v248, v42
	ds_bpermute_b32 v217, v248, v43
	ds_bpermute_b32 v218, v248, v44
	ds_bpermute_b32 v219, v248, v45
	v_mov_b32_e32 v228, v48
	v_mov_b32_e32 v229, v49
	s_waitcnt lgkmcnt(4)
	global_store_dwordx4 v[226:227], v[212:215], off offset:256
	s_nop 1
	v_pk_add_f32 v[42:43], v[32:33], 0 op_sel_hi:[1,0]
	v_pk_add_f32 v[32:33], v[30:31], 0 op_sel_hi:[1,0]
	v_cvt_pk_bf16_f32 v30, v38, v39
	v_cvt_pk_bf16_f32 v31, v40, v41
	s_nop 0
	v_cvt_pk_bf16_f32 v32, v32, v33
	v_cvt_pk_bf16_f32 v33, v42, v43
	ds_bpermute_b32 v220, v248, v30
	ds_bpermute_b32 v221, v248, v31
	ds_bpermute_b32 v222, v248, v32
	ds_bpermute_b32 v223, v248, v33
	v_mov_b32_e32 v230, v46
	v_mov_b32_e32 v231, v47
	s_waitcnt lgkmcnt(4)
	global_store_dwordx4 v[228:229], v[216:219], off
	s_nop 1
	v_lshl_add_u64 v[30:31], v[140:141], 0, s[16:17]
	v_pk_add_f32 v[32:33], v[36:37], 0 op_sel_hi:[1,0]
	s_mov_b32 s16, 0x50000
	v_pk_add_f32 v[36:37], v[28:29], 0 op_sel_hi:[1,0]
	v_pk_add_f32 v[28:29], v[26:27], 0 op_sel_hi:[1,0]
	v_cvt_pk_bf16_f32 v26, v34, v35
	v_cvt_pk_bf16_f32 v27, v32, v33
	v_add_co_u32_e32 v32, vcc, s16, v140
	v_cvt_pk_bf16_f32 v28, v28, v29
	v_cvt_pk_bf16_f32 v29, v36, v37
	s_mov_b64 s[16:17], 0x58000
	s_nop 0
	v_addc_co_u32_e32 v33, vcc, 0, v141, vcc
	ds_bpermute_b32 v208, v248, v26
	ds_bpermute_b32 v209, v248, v27
	ds_bpermute_b32 v210, v248, v28
	ds_bpermute_b32 v211, v248, v29
	v_mov_b32_e32 v224, v32
	v_mov_b32_e32 v225, v33
	s_waitcnt lgkmcnt(4)
	global_store_dwordx4 v[230:231], v[220:223], off offset:256
	s_nop 1
	v_pk_add_f32 v[26:27], v[16:17], 0 op_sel_hi:[1,0]
	v_pk_add_f32 v[16:17], v[14:15], 0 op_sel_hi:[1,0]
	v_cvt_pk_bf16_f32 v14, v22, v23
	v_cvt_pk_bf16_f32 v15, v24, v25
	s_nop 0
	v_cvt_pk_bf16_f32 v16, v16, v17
	v_cvt_pk_bf16_f32 v17, v26, v27
	ds_bpermute_b32 v212, v248, v14
	ds_bpermute_b32 v213, v248, v15
	ds_bpermute_b32 v214, v248, v16
	ds_bpermute_b32 v215, v248, v17
	v_mov_b32_e32 v226, v30
	v_mov_b32_e32 v227, v31
	s_waitcnt lgkmcnt(4)
	global_store_dwordx4 v[224:225], v[208:211], off
	s_nop 1
	v_lshl_add_u64 v[14:15], v[140:141], 0, s[16:17]
	v_pk_add_f32 v[16:17], v[20:21], 0 op_sel_hi:[1,0]
	s_mov_b32 s16, 0x58000
	v_pk_add_f32 v[20:21], v[12:13], 0 op_sel_hi:[1,0]
	v_pk_add_f32 v[12:13], v[10:11], 0 op_sel_hi:[1,0]
	v_cvt_pk_bf16_f32 v10, v18, v19
	v_cvt_pk_bf16_f32 v11, v16, v17
	v_add_co_u32_e32 v16, vcc, s16, v140
	v_cvt_pk_bf16_f32 v12, v12, v13
	v_cvt_pk_bf16_f32 v13, v20, v21
	s_mov_b64 s[16:17], -1
	s_nop 0
	v_addc_co_u32_e32 v17, vcc, 0, v141, vcc
	ds_bpermute_b32 v216, v248, v10
	ds_bpermute_b32 v217, v248, v11
	ds_bpermute_b32 v218, v248, v12
	ds_bpermute_b32 v219, v248, v13
	v_mov_b32_e32 v228, v16
	v_mov_b32_e32 v229, v17
	s_waitcnt lgkmcnt(4)
	global_store_dwordx4 v[226:227], v[212:215], off offset:256
	s_andn2_b64 vcc, exec, s[38:39]
	s_nop 0
	v_pk_add_f32 v[10:11], v[4:5], 0 op_sel_hi:[1,0]
	v_pk_add_f32 v[4:5], v[2:3], 0 op_sel_hi:[1,0]
	v_cvt_pk_bf16_f32 v2, v6, v7
	v_cvt_pk_bf16_f32 v3, v8, v9
	s_nop 0
	v_cvt_pk_bf16_f32 v4, v4, v5
	v_cvt_pk_bf16_f32 v5, v10, v11
	ds_bpermute_b32 v220, v248, v2
	ds_bpermute_b32 v221, v248, v3
	ds_bpermute_b32 v222, v248, v4
	ds_bpermute_b32 v223, v248, v5
	v_mov_b32_e32 v230, v14
	v_mov_b32_e32 v231, v15
	s_waitcnt lgkmcnt(4)
	global_store_dwordx4 v[228:229], v[216:219], off
	s_waitcnt lgkmcnt(0)
	global_store_dwordx4 v[230:231], v[220:223], off offset:256
	s_cbranch_vccnz .LBB0_435
	s_andn2_b64 vcc, exec, s[0:1]
	s_cbranch_vccnz .LBB0_434
	s_barrier
	s_branch .LBB0_434

; __device__ __forceinline__ unsigned cvt_pk_bf16(float lo, float hi) { unsigned r; asm volatile("v_cvt_pk_bf16_f32 %0, %1, %2" : "=v"(r) : "v"(lo), "v"(hi)); return r; }
;     __device__ __forceinline__ void operator()(const f32x4 (&acc)[2][2][4][2], const Unit& u, int wr, int wc, int fr, int fq) const {
;     ...
; #pragma unroll
;         for (int ai = 0; ai < 2; ++ai)
; #pragma unroll
;             for (int m = 0; m < 4; ++m) {
;                 bf16_t* rowp = O + (size_t)(row0 + ai * HALF + m * 16) * DFF + col0;
;                 f32x2 G[4], U[4], t[4], r[4];
; #pragma unroll
;                 for (int n = 0; n < 2; ++n) { G[2 * n] = (f32x2){acc[ai][0][m][n][0], acc[ai][0][m][n][1]}; G[2 * n + 1] = (f32x2){acc[ai][0][m][n][2], acc[ai][0][m][n][3]};
;                                               U[2 * n] = (f32x2){acc[ai][1][m][n][0], acc[ai][1][m][n][1]}; U[2 * n + 1] = (f32x2){acc[ai][1][m][n][2], acc[ai][1][m][n][3]}; }
; #pragma unroll
;                 for (int q = 0; q < 4; ++q) { t[q].x = __builtin_amdgcn_exp2f(G[q].x); t[q].y = __builtin_amdgcn_exp2f(G[q].y); }
; #pragma unroll
;                 for (int q = 0; q < 4; ++q) { t[q] = t[q] + 1.0f; r[q] = G[q] * U[q]; }
; #pragma unroll
;                 for (int q = 0; q < 4; ++q) { t[q].x = __builtin_amdgcn_rcpf(t[q].x); t[q].y = __builtin_amdgcn_rcpf(t[q].y); }
; #pragma unroll
;                 for (int q = 0; q < 4; ++q) r[q] = r[q] * t[q];
;                 u32x4 w; w.x = cvt_pk_bf16(r[0].x, r[0].y); w.y = cvt_pk_bf16(r[1].x, r[1].y); w.z = cvt_pk_bf16(r[2].x, r[2].y); w.w = cvt_pk_bf16(r[3].x, r[3].y);
;                 *(u32x4*)rowp = w;
.LBB0_583:
	v_exp_f32_e32 v152, v126
	v_exp_f32_e32 v153, v127
	v_exp_f32_e32 v156, v122
	v_exp_f32_e32 v157, v123
	v_exp_f32_e32 v154, v128
	v_exp_f32_e32 v155, v129
	v_exp_f32_e32 v158, v124
	v_exp_f32_e32 v159, v125
	v_pk_add_f32 v[152:153], v[152:153], 1.0 op_sel_hi:[1,0]
	v_pk_mul_f32 v[120:121], v[128:129], v[120:121]
	v_pk_add_f32 v[128:129], v[156:157], 1.0 op_sel_hi:[1,0]
	v_pk_mul_f32 v[118:119], v[126:127], v[118:119]
	v_pk_add_f32 v[126:127], v[154:155], 1.0 op_sel_hi:[1,0]
	v_pk_mul_f32 v[116:117], v[124:125], v[116:117]
	v_pk_mul_f32 v[114:115], v[122:123], v[114:115]
	v_pk_add_f32 v[122:123], v[158:159], 1.0 op_sel_hi:[1,0]
	v_rcp_f32_e32 v124, v152
	v_rcp_f32_e32 v125, v153
	v_rcp_f32_e32 v128, v128
	v_rcp_f32_e32 v129, v129
	v_rcp_f32_e32 v126, v126
	v_rcp_f32_e32 v127, v127
	v_rcp_f32_e32 v122, v122
	v_rcp_f32_e32 v123, v123
	v_lshl_or_b32 v148, s65, 7, v144
	v_lshl_add_u32 v146, s72, 8, v142
	v_ashrrev_i32_e32 v149, 31, v148
	v_mov_b64_e32 v[140:141], s[74:75]
	v_mad_i64_i32 v[150:151], s[16:17], v146, s87, v[140:141]
	v_pk_mul_f32 v[118:119], v[124:125], v[118:119]
	v_pk_mul_f32 v[124:125], v[128:129], v[114:115]
	v_lshlrev_b64 v[114:115], 1, v[148:149]
	v_pk_mul_f32 v[120:121], v[126:127], v[120:121]
	v_pk_mul_f32 v[122:123], v[122:123], v[116:117]
	v_lshl_add_u64 v[126:127], v[150:151], 0, v[114:115]
	v_cvt_pk_bf16_f32 v116, v118, v119
	v_cvt_pk_bf16_f32 v117, v120, v121
	v_cvt_pk_bf16_f32 v118, v124, v125
	v_cvt_pk_bf16_f32 v119, v122, v123
	ds_bpermute_b32 v208, v248, v116
	ds_bpermute_b32 v209, v248, v117
	ds_bpermute_b32 v210, v248, v118
	ds_bpermute_b32 v211, v248, v119
	v_mov_b32_e32 v224, v126
	v_mov_b32_e32 v225, v127
	v_exp_f32_e32 v120, v112
	v_exp_f32_e32 v121, v113
	v_exp_f32_e32 v118, v110
	v_exp_f32_e32 v119, v111
	v_exp_f32_e32 v122, v106
	v_exp_f32_e32 v123, v107
	v_exp_f32_e32 v124, v108
	v_exp_f32_e32 v125, v109
	v_pk_add_f32 v[118:119], v[118:119], 1.0 op_sel_hi:[1,0]
	v_pk_mul_f32 v[104:105], v[112:113], v[104:105]
	v_pk_mul_f32 v[102:103], v[110:111], v[102:103]
	v_pk_add_f32 v[110:111], v[120:121], 1.0 op_sel_hi:[1,0]
	v_pk_add_f32 v[112:113], v[122:123], 1.0 op_sel_hi:[1,0]
	v_pk_mul_f32 v[98:99], v[106:107], v[98:99]
	v_pk_add_f32 v[106:107], v[124:125], 1.0 op_sel_hi:[1,0]
	v_pk_mul_f32 v[100:101], v[108:109], v[100:101]
	v_rcp_f32_e32 v108, v118
	v_rcp_f32_e32 v109, v119
	v_rcp_f32_e32 v110, v110
	v_rcp_f32_e32 v111, v111
	v_rcp_f32_e32 v112, v112
	v_rcp_f32_e32 v113, v113
	v_rcp_f32_e32 v106, v106
	v_rcp_f32_e32 v107, v107
	v_or_b32_e32 v116, 16, v146
	v_mad_i64_i32 v[116:117], s[16:17], v116, s87, v[140:141]
	v_pk_mul_f32 v[102:103], v[108:109], v[102:103]
	v_pk_mul_f32 v[104:105], v[110:111], v[104:105]
	v_pk_mul_f32 v[108:109], v[112:113], v[98:99]
	v_pk_mul_f32 v[106:107], v[106:107], v[100:101]
	v_lshl_add_u64 v[110:111], v[116:117], 0, v[114:115]
	v_cvt_pk_bf16_f32 v98, v102, v103
	v_cvt_pk_bf16_f32 v99, v104, v105
	v_cvt_pk_bf16_f32 v100, v108, v109
	v_cvt_pk_bf16_f32 v101, v106, v107
	ds_bpermute_b32 v212, v248, v98
	ds_bpermute_b32 v213, v248, v99
	ds_bpermute_b32 v214, v248, v100
	ds_bpermute_b32 v215, v248, v101
	v_mov_b32_e32 v226, v110
	v_mov_b32_e32 v227, v111
	s_waitcnt lgkmcnt(4)
	global_store_dwordx4 v[224:225], v[208:211], off
	v_exp_f32_e32 v102, v96
	v_exp_f32_e32 v103, v97
	v_exp_f32_e32 v100, v94
	v_exp_f32_e32 v101, v95
	v_exp_f32_e32 v104, v90
	v_exp_f32_e32 v105, v91
	v_exp_f32_e32 v106, v92
	v_exp_f32_e32 v107, v93
	v_pk_add_f32 v[100:101], v[100:101], 1.0 op_sel_hi:[1,0]
	v_pk_mul_f32 v[88:89], v[96:97], v[88:89]
	v_pk_mul_f32 v[86:87], v[94:95], v[86:87]
	v_pk_add_f32 v[94:95], v[102:103], 1.0 op_sel_hi:[1,0]
	v_pk_add_f32 v[96:97], v[104:105], 1.0 op_sel_hi:[1,0]
	v_pk_mul_f32 v[82:83], v[90:91], v[82:83]
	v_pk_add_f32 v[90:91], v[106:107], 1.0 op_sel_hi:[1,0]
	v_pk_mul_f32 v[84:85], v[92:93], v[84:85]
	v_rcp_f32_e32 v92, v100
	v_rcp_f32_e32 v93, v101
	v_rcp_f32_e32 v94, v94
	v_rcp_f32_e32 v95, v95
	v_rcp_f32_e32 v96, v96
	v_rcp_f32_e32 v97, v97
	v_rcp_f32_e32 v90, v90
	v_rcp_f32_e32 v91, v91
	v_or_b32_e32 v98, 32, v146
	v_mad_i64_i32 v[98:99], s[16:17], v98, s87, v[140:141]
	v_pk_mul_f32 v[86:87], v[92:93], v[86:87]
	v_pk_mul_f32 v[88:89], v[94:95], v[88:89]
	v_pk_mul_f32 v[92:93], v[96:97], v[82:83]
	v_pk_mul_f32 v[90:91], v[90:91], v[84:85]
	v_lshl_add_u64 v[94:95], v[98:99], 0, v[114:115]
	v_cvt_pk_bf16_f32 v82, v86, v87
	v_cvt_pk_bf16_f32 v83, v88, v89
	v_cvt_pk_bf16_f32 v84, v92, v93
	v_cvt_pk_bf16_f32 v85, v90, v91
	ds_bpermute_b32 v216, v248, v82
	ds_bpermute_b32 v217, v248, v83
	ds_bpermute_b32 v218, v248, v84
	ds_bpermute_b32 v219, v248, v85
	v_mov_b32_e32 v228, v94
	v_mov_b32_e32 v229, v95
	s_waitcnt lgkmcnt(4)
	global_store_dwordx4 v[226:227], v[212:215], off
	v_exp_f32_e32 v86, v80
	v_exp_f32_e32 v87, v81
	v_exp_f32_e32 v84, v78
	v_exp_f32_e32 v85, v79
	v_exp_f32_e32 v88, v74
	v_exp_f32_e32 v89, v75
	v_exp_f32_e32 v90, v76
	v_exp_f32_e32 v91, v77
	v_pk_add_f32 v[84:85], v[84:85], 1.0 op_sel_hi:[1,0]
	v_pk_mul_f32 v[72:73], v[80:81], v[72:73]
	v_pk_mul_f32 v[70:71], v[78:79], v[70:71]
	v_pk_add_f32 v[78:79], v[86:87], 1.0 op_sel_hi:[1,0]
	v_pk_add_f32 v[80:81], v[88:89], 1.0 op_sel_hi:[1,0]
	v_pk_mul_f32 v[66:67], v[74:75], v[66:67]
	v_pk_add_f32 v[74:75], v[90:91], 1.0 op_sel_hi:[1,0]
	v_pk_mul_f32 v[68:69], v[76:77], v[68:69]
	v_rcp_f32_e32 v76, v84
	v_rcp_f32_e32 v77, v85
	v_rcp_f32_e32 v78, v78
	v_rcp_f32_e32 v79, v79
	v_rcp_f32_e32 v80, v80
	v_rcp_f32_e32 v81, v81
	v_rcp_f32_e32 v74, v74
	v_rcp_f32_e32 v75, v75
	v_or_b32_e32 v82, 48, v146
	v_mad_i64_i32 v[82:83], s[16:17], v82, s87, v[140:141]
	v_pk_mul_f32 v[70:71], v[76:77], v[70:71]
	v_pk_mul_f32 v[72:73], v[78:79], v[72:73]
	v_pk_mul_f32 v[76:77], v[80:81], v[66:67]
	v_pk_mul_f32 v[74:75], v[74:75], v[68:69]
	v_lshl_add_u64 v[78:79], v[82:83], 0, v[114:115]
	v_cvt_pk_bf16_f32 v66, v70, v71
	v_cvt_pk_bf16_f32 v67, v72, v73
	v_cvt_pk_bf16_f32 v68, v76, v77
	v_cvt_pk_bf16_f32 v69, v74, v75
	ds_bpermute_b32 v220, v248, v66
	ds_bpermute_b32 v221, v248, v67
	ds_bpermute_b32 v222, v248, v68
	ds_bpermute_b32 v223, v248, v69
	v_mov_b32_e32 v230, v78
	v_mov_b32_e32 v231, v79
	s_waitcnt lgkmcnt(4)
; __device__ __forceinline__ unsigned cvt_pk_bf16(float lo, float hi) { unsigned r; asm volatile("v_cvt_pk_bf16_f32 %0, %1, %2" : "=v"(r) : "v"(lo), "v"(hi)); return r; }
;     ...
;         if constexpr (!Epi::AFTER_DRAIN) { E(acc, cur, wr, wc, fr, fq); S.done(cur); }
;         if (!has_next) break;
;     __device__ __forceinline__ void operator()(const f32x4 (&acc)[2][2][4][2], const Unit& u, int wr, int wc, int fr, int fq) const {
;     ...
; #pragma unroll
;         for (int ai = 0; ai < 2; ++ai)
; #pragma unroll
;             for (int m = 0; m < 4; ++m) {
;                 bf16_t* rowp = O + (size_t)(row0 + ai * HALF + m * 16) * DFF + col0;
;                 f32x2 G[4], U[4], t[4], r[4];
; #pragma unroll
;                 for (int n = 0; n < 2; ++n) { G[2 * n] = (f32x2){acc[ai][0][m][n][0], acc[ai][0][m][n][1]}; G[2 * n + 1] = (f32x2){acc[ai][0][m][n][2], acc[ai][0][m][n][3]};
;                                               U[2 * n] = (f32x2){acc[ai][1][m][n][0], acc[ai][1][m][n][1]}; U[2 * n + 1] = (f32x2){acc[ai][1][m][n][2], acc[ai][1][m][n][3]}; }
; #pragma unroll
;                 for (int q = 0; q < 4; ++q) { t[q].x = __builtin_amdgcn_exp2f(G[q].x); t[q].y = __builtin_amdgcn_exp2f(G[q].y); }
; #pragma unroll
;                 for (int q = 0; q < 4; ++q) { t[q] = t[q] + 1.0f; r[q] = G[q] * U[q]; }
; #pragma unroll
;                 for (int q = 0; q < 4; ++q) { t[q].x = __builtin_amdgcn_rcpf(t[q].x); t[q].y = __builtin_amdgcn_rcpf(t[q].y); }
; #pragma unroll
;                 for (int q = 0; q < 4; ++q) r[q] = r[q] * t[q];
;                 u32x4 w; w.x = cvt_pk_bf16(r[0].x, r[0].y); w.y = cvt_pk_bf16(r[1].x, r[1].y); w.z = cvt_pk_bf16(r[2].x, r[2].y); w.w = cvt_pk_bf16(r[3].x, r[3].y);
;                 *(u32x4*)rowp = w;
	global_store_dwordx4 v[228:229], v[216:219], off
	v_exp_f32_e32 v70, v64
	v_exp_f32_e32 v71, v65
	v_exp_f32_e32 v68, v62
	v_exp_f32_e32 v69, v63
	v_exp_f32_e32 v72, v58
	v_exp_f32_e32 v73, v59
	v_exp_f32_e32 v74, v60
	v_exp_f32_e32 v75, v61
	v_pk_add_f32 v[68:69], v[68:69], 1.0 op_sel_hi:[1,0]
	v_pk_mul_f32 v[56:57], v[64:65], v[56:57]
	v_pk_mul_f32 v[54:55], v[62:63], v[54:55]
	v_pk_add_f32 v[62:63], v[70:71], 1.0 op_sel_hi:[1,0]
	v_pk_add_f32 v[64:65], v[72:73], 1.0 op_sel_hi:[1,0]
	v_pk_mul_f32 v[50:51], v[58:59], v[50:51]
	v_pk_add_f32 v[58:59], v[74:75], 1.0 op_sel_hi:[1,0]
	v_pk_mul_f32 v[52:53], v[60:61], v[52:53]
	v_rcp_f32_e32 v60, v68
	v_rcp_f32_e32 v61, v69
	v_rcp_f32_e32 v62, v62
	v_rcp_f32_e32 v63, v63
	v_rcp_f32_e32 v64, v64
	v_rcp_f32_e32 v65, v65
	v_rcp_f32_e32 v58, v58
	v_rcp_f32_e32 v59, v59
	v_add_u32_e32 v66, 0x80, v146
	v_mad_i64_i32 v[66:67], s[16:17], v66, s87, v[140:141]
	v_pk_mul_f32 v[54:55], v[60:61], v[54:55]
	v_pk_mul_f32 v[56:57], v[62:63], v[56:57]
	v_pk_mul_f32 v[60:61], v[64:65], v[50:51]
	v_pk_mul_f32 v[58:59], v[58:59], v[52:53]
	v_lshl_add_u64 v[62:63], v[66:67], 0, v[114:115]
	v_cvt_pk_bf16_f32 v50, v54, v55
	v_cvt_pk_bf16_f32 v51, v56, v57
	v_cvt_pk_bf16_f32 v52, v60, v61
	v_cvt_pk_bf16_f32 v53, v58, v59
	ds_bpermute_b32 v208, v248, v50
	ds_bpermute_b32 v209, v248, v51
	ds_bpermute_b32 v210, v248, v52
	ds_bpermute_b32 v211, v248, v53
	v_mov_b32_e32 v224, v62
	v_mov_b32_e32 v225, v63
	s_waitcnt lgkmcnt(4)
	global_store_dwordx4 v[230:231], v[220:223], off
	v_exp_f32_e32 v54, v48
	v_exp_f32_e32 v55, v49
	v_exp_f32_e32 v52, v46
	v_exp_f32_e32 v53, v47
	v_exp_f32_e32 v56, v42
	v_exp_f32_e32 v57, v43
	v_exp_f32_e32 v58, v44
	v_exp_f32_e32 v59, v45
	v_pk_add_f32 v[52:53], v[52:53], 1.0 op_sel_hi:[1,0]
	v_pk_mul_f32 v[40:41], v[48:49], v[40:41]
	v_pk_mul_f32 v[38:39], v[46:47], v[38:39]
	v_pk_add_f32 v[46:47], v[54:55], 1.0 op_sel_hi:[1,0]
	v_pk_add_f32 v[48:49], v[56:57], 1.0 op_sel_hi:[1,0]
	v_pk_mul_f32 v[34:35], v[42:43], v[34:35]
	v_pk_add_f32 v[42:43], v[58:59], 1.0 op_sel_hi:[1,0]
	v_pk_mul_f32 v[36:37], v[44:45], v[36:37]
	v_rcp_f32_e32 v44, v52
	v_rcp_f32_e32 v45, v53
	v_rcp_f32_e32 v46, v46
	v_rcp_f32_e32 v47, v47
	v_rcp_f32_e32 v48, v48
	v_rcp_f32_e32 v49, v49
	v_rcp_f32_e32 v42, v42
	v_rcp_f32_e32 v43, v43
	v_add_u32_e32 v50, 0x90, v146
	v_mad_i64_i32 v[50:51], s[16:17], v50, s87, v[140:141]
	v_pk_mul_f32 v[38:39], v[44:45], v[38:39]
	v_pk_mul_f32 v[40:41], v[46:47], v[40:41]
	v_pk_mul_f32 v[44:45], v[48:49], v[34:35]
	v_pk_mul_f32 v[42:43], v[42:43], v[36:37]
	v_lshl_add_u64 v[46:47], v[50:51], 0, v[114:115]
	v_cvt_pk_bf16_f32 v34, v38, v39
	v_cvt_pk_bf16_f32 v35, v40, v41
	v_cvt_pk_bf16_f32 v36, v44, v45
	v_cvt_pk_bf16_f32 v37, v42, v43
	ds_bpermute_b32 v212, v248, v34
	ds_bpermute_b32 v213, v248, v35
	ds_bpermute_b32 v214, v248, v36
	ds_bpermute_b32 v215, v248, v37
	v_mov_b32_e32 v226, v46
	v_mov_b32_e32 v227, v47
	s_waitcnt lgkmcnt(4)
	global_store_dwordx4 v[224:225], v[208:211], off
	v_exp_f32_e32 v38, v32
	v_exp_f32_e32 v39, v33
	v_exp_f32_e32 v36, v30
	v_exp_f32_e32 v37, v31
	v_exp_f32_e32 v40, v26
	v_exp_f32_e32 v41, v27
	v_exp_f32_e32 v42, v28
	v_exp_f32_e32 v43, v29
	v_pk_add_f32 v[36:37], v[36:37], 1.0 op_sel_hi:[1,0]
	v_pk_mul_f32 v[24:25], v[32:33], v[24:25]
	v_pk_mul_f32 v[22:23], v[30:31], v[22:23]
	v_pk_add_f32 v[30:31], v[38:39], 1.0 op_sel_hi:[1,0]
	v_pk_add_f32 v[32:33], v[40:41], 1.0 op_sel_hi:[1,0]
	v_pk_mul_f32 v[20:21], v[28:29], v[20:21]
	v_pk_mul_f32 v[18:19], v[26:27], v[18:19]
	v_pk_add_f32 v[26:27], v[42:43], 1.0 op_sel_hi:[1,0]
	v_rcp_f32_e32 v28, v36
	v_rcp_f32_e32 v29, v37
	v_rcp_f32_e32 v30, v30
	v_rcp_f32_e32 v31, v31
	v_rcp_f32_e32 v32, v32
	v_rcp_f32_e32 v33, v33
	v_rcp_f32_e32 v26, v26
	v_rcp_f32_e32 v27, v27
	v_add_u32_e32 v34, 0xa0, v146
	v_mad_i64_i32 v[34:35], s[16:17], v34, s87, v[140:141]
	v_pk_mul_f32 v[22:23], v[28:29], v[22:23]
	v_pk_mul_f32 v[24:25], v[30:31], v[24:25]
	v_pk_mul_f32 v[28:29], v[32:33], v[18:19]
	v_pk_mul_f32 v[26:27], v[26:27], v[20:21]
	v_lshl_add_u64 v[30:31], v[34:35], 0, v[114:115]
	v_cvt_pk_bf16_f32 v18, v22, v23
	v_cvt_pk_bf16_f32 v19, v24, v25
	v_cvt_pk_bf16_f32 v20, v28, v29
	v_cvt_pk_bf16_f32 v21, v26, v27
	v_exp_f32_e32 v22, v16
	v_exp_f32_e32 v23, v17
	ds_bpermute_b32 v216, v248, v18
	ds_bpermute_b32 v217, v248, v19
	ds_bpermute_b32 v218, v248, v20
	ds_bpermute_b32 v219, v248, v21
	v_mov_b32_e32 v228, v30
	v_mov_b32_e32 v229, v31
	s_waitcnt lgkmcnt(4)
	global_store_dwordx4 v[226:227], v[212:215], off
	v_exp_f32_e32 v24, v10
	v_exp_f32_e32 v25, v11
	v_exp_f32_e32 v20, v14
	v_exp_f32_e32 v21, v15
	v_exp_f32_e32 v26, v12
	v_exp_f32_e32 v27, v13
	v_pk_mul_f32 v[6:7], v[14:15], v[6:7]
	v_pk_add_f32 v[14:15], v[22:23], 1.0 op_sel_hi:[1,0]
	v_pk_add_f32 v[20:21], v[20:21], 1.0 op_sel_hi:[1,0]
	v_pk_mul_f32 v[8:9], v[16:17], v[8:9]
	v_pk_add_f32 v[16:17], v[24:25], 1.0 op_sel_hi:[1,0]
	v_pk_mul_f32 v[2:3], v[10:11], v[2:3]
	v_pk_add_f32 v[10:11], v[26:27], 1.0 op_sel_hi:[1,0]
	v_rcp_f32_e32 v14, v14
	v_rcp_f32_e32 v15, v15
	v_pk_mul_f32 v[4:5], v[12:13], v[4:5]
	v_rcp_f32_e32 v12, v20
	v_rcp_f32_e32 v13, v21
	v_rcp_f32_e32 v16, v16
	v_rcp_f32_e32 v17, v17
	v_rcp_f32_e32 v10, v10
	v_rcp_f32_e32 v11, v11
	v_add_u32_e32 v18, 0xb0, v146
	v_mad_i64_i32 v[18:19], s[16:17], v18, s87, v[140:141]
	v_pk_mul_f32 v[8:9], v[14:15], v[8:9]
	v_lshl_add_u64 v[14:15], v[18:19], 0, v[114:115]
	s_andn2_b64 vcc, exec, s[40:41]
	s_mov_b64 s[16:17], -1
	v_pk_mul_f32 v[6:7], v[12:13], v[6:7]
	v_pk_mul_f32 v[12:13], v[16:17], v[2:3]
	v_pk_mul_f32 v[10:11], v[10:11], v[4:5]
	v_cvt_pk_bf16_f32 v2, v6, v7
	v_cvt_pk_bf16_f32 v3, v8, v9
	v_cvt_pk_bf16_f32 v4, v12, v13
	s_nop 0
	v_cvt_pk_bf16_f32 v5, v10, v11
	ds_bpermute_b32 v220, v248, v2
	ds_bpermute_b32 v221, v248, v3
	ds_bpermute_b32 v222, v248, v4
	ds_bpermute_b32 v223, v248, v5
	v_mov_b32_e32 v230, v14
	v_mov_b32_e32 v231, v15
	s_waitcnt lgkmcnt(4)
	global_store_dwordx4 v[228:229], v[216:219], off
	s_waitcnt lgkmcnt(0)
	global_store_dwordx4 v[230:231], v[220:223], off
	s_cbranch_vccnz .LBB0_576
	s_andn2_b64 vcc, exec, s[0:1]
	s_cbranch_vccnz .LBB0_575
	s_barrier
	s_branch .LBB0_575

; __device__ __forceinline__ unsigned cvt_pk_bf16(float lo, float hi) { unsigned r; asm volatile("v_cvt_pk_bf16_f32 %0, %1, %2" : "=v"(r) : "v"(lo), "v"(hi)); return r; }
;     __device__ __forceinline__ void operator()(const f32x4 (&acc)[2][2][4][2], const Unit& u, int wr, int wc, int fr, int fq) const {
;     ...
;         for (int ai = 0; ai < 2; ++ai)
; #pragma unroll
;             for (int m = 0; m < 4; ++m) { bf16_t* rowp = base + (size_t)(row0 + ai * HALF + m * 16) * ldc + col0;
; #pragma unroll
;                 for (int bj = 0; bj < 2; ++bj) { f32x4 v0 = acc[ai][bj][m][0] + bv[bj][0], v1 = acc[ai][bj][m][1] + bv[bj][1];
;                     if (ACT == 1) { f32x2 a = gelu_pk((f32x2){v0[0], v0[1]}), b = gelu_pk((f32x2){v0[2], v0[3]}), c = gelu_pk((f32x2){v1[0], v1[1]}), d = gelu_pk((f32x2){v1[2], v1[3]});
;                         v0 = (f32x4){a.x, a.y, b.x, b.y}; v1 = (f32x4){c.x, c.y, d.x, d.y}; }
;                     v0 = v0 * sc; v1 = v1 * sc; u32x4 w; w.x = cvt_pk_bf16(v0[0], v0[1]); w.y = cvt_pk_bf16(v0[2], v0[3]); w.z = cvt_pk_bf16(v1[0], v1[1]); w.w = cvt_pk_bf16(v1[2], v1[3]);
;                     *(u32x4*)(rowp + bj * HALF) = w; } }
.LBB0_659:
	v_lshl_add_u32 v146, s72, 8, v142
	v_lshl_or_b32 v140, s65, 8, v144
	v_ashrrev_i32_e32 v141, 31, v140
	v_ashrrev_i32_e32 v147, 31, v146
	v_lshl_add_u64 v[148:149], v[140:141], 1, s[82:83]
	v_lshlrev_b64 v[140:141], 11, v[146:147]
	v_lshl_add_u64 v[140:141], v[148:149], 0, v[140:141]
	v_pk_add_f32 v[128:129], v[128:129], 0 op_sel_hi:[1,0]
	v_pk_add_f32 v[126:127], v[126:127], 0 op_sel_hi:[1,0]
	v_pk_add_f32 v[150:151], v[124:125], 0 op_sel_hi:[1,0]
	v_pk_add_f32 v[124:125], v[122:123], 0 op_sel_hi:[1,0]
	v_cvt_pk_bf16_f32 v122, v126, v127
	v_cvt_pk_bf16_f32 v123, v128, v129
	v_pk_add_f32 v[118:119], v[118:119], 0 op_sel_hi:[1,0]
	v_cvt_pk_bf16_f32 v124, v124, v125
	v_cvt_pk_bf16_f32 v125, v150, v151
	ds_bpermute_b32 v208, v248, v122
	ds_bpermute_b32 v209, v248, v123
	ds_bpermute_b32 v210, v248, v124
	ds_bpermute_b32 v211, v248, v125
	v_mov_b32_e32 v224, v140
	v_mov_b32_e32 v225, v141
	v_pk_add_f32 v[120:121], v[120:121], 0 op_sel_hi:[1,0]
	v_pk_add_f32 v[114:115], v[114:115], 0 op_sel_hi:[1,0]
	v_pk_add_f32 v[122:123], v[112:113], 0 op_sel_hi:[1,0]
	v_pk_add_f32 v[112:113], v[110:111], 0 op_sel_hi:[1,0]
	v_cvt_pk_bf16_f32 v110, v118, v119
	v_cvt_pk_bf16_f32 v111, v120, v121
	v_pk_add_f32 v[102:103], v[102:103], 0 op_sel_hi:[1,0]
	v_cvt_pk_bf16_f32 v112, v112, v113
	v_cvt_pk_bf16_f32 v113, v122, v123
	ds_bpermute_b32 v212, v248, v110
	ds_bpermute_b32 v213, v248, v111
	ds_bpermute_b32 v214, v248, v112
	ds_bpermute_b32 v215, v248, v113
	v_mov_b32_e32 v226, v140
	v_mov_b32_e32 v227, v141
	s_waitcnt lgkmcnt(4)
	global_store_dwordx4 v[224:225], v[208:211], off
	v_pk_add_f32 v[104:105], v[104:105], 0 op_sel_hi:[1,0]
	v_pk_add_f32 v[98:99], v[98:99], 0 op_sel_hi:[1,0]
	v_or_b32_e32 v110, 16, v146
	v_ashrrev_i32_e32 v111, 31, v110
	v_lshlrev_b64 v[110:111], 11, v[110:111]
	v_lshl_add_u64 v[110:111], v[148:149], 0, v[110:111]
	v_pk_add_f32 v[112:113], v[116:117], 0 op_sel_hi:[1,0]
	v_pk_add_f32 v[116:117], v[108:109], 0 op_sel_hi:[1,0]
	v_pk_add_f32 v[108:109], v[106:107], 0 op_sel_hi:[1,0]
	v_cvt_pk_bf16_f32 v106, v114, v115
	v_cvt_pk_bf16_f32 v107, v112, v113
	v_pk_add_f32 v[86:87], v[86:87], 0 op_sel_hi:[1,0]
	v_cvt_pk_bf16_f32 v108, v108, v109
	v_cvt_pk_bf16_f32 v109, v116, v117
	ds_bpermute_b32 v216, v248, v106
	ds_bpermute_b32 v217, v248, v107
	ds_bpermute_b32 v218, v248, v108
	ds_bpermute_b32 v219, v248, v109
	v_mov_b32_e32 v228, v110
	v_mov_b32_e32 v229, v111
	s_waitcnt lgkmcnt(4)
	global_store_dwordx4 v[226:227], v[212:215], off offset:256
	v_pk_add_f32 v[88:89], v[88:89], 0 op_sel_hi:[1,0]
	v_pk_add_f32 v[82:83], v[82:83], 0 op_sel_hi:[1,0]
	v_pk_add_f32 v[106:107], v[96:97], 0 op_sel_hi:[1,0]
	v_pk_add_f32 v[96:97], v[94:95], 0 op_sel_hi:[1,0]
	v_cvt_pk_bf16_f32 v94, v102, v103
	v_cvt_pk_bf16_f32 v95, v104, v105
	v_pk_add_f32 v[72:73], v[72:73], 0 op_sel_hi:[1,0]
	v_cvt_pk_bf16_f32 v96, v96, v97
	v_cvt_pk_bf16_f32 v97, v106, v107
	ds_bpermute_b32 v220, v248, v94
	ds_bpermute_b32 v221, v248, v95
	ds_bpermute_b32 v222, v248, v96
	ds_bpermute_b32 v223, v248, v97
	v_mov_b32_e32 v230, v110
	v_mov_b32_e32 v231, v111
	s_waitcnt lgkmcnt(4)
	global_store_dwordx4 v[228:229], v[216:219], off
	v_pk_add_f32 v[70:71], v[70:71], 0 op_sel_hi:[1,0]
	s_mov_b64 s[16:17], 0x40000
	v_or_b32_e32 v94, 32, v146
	v_ashrrev_i32_e32 v95, 31, v94
	v_lshlrev_b64 v[94:95], 11, v[94:95]
	v_lshl_add_u64 v[94:95], v[148:149], 0, v[94:95]
	v_pk_add_f32 v[96:97], v[100:101], 0 op_sel_hi:[1,0]
	v_pk_add_f32 v[100:101], v[92:93], 0 op_sel_hi:[1,0]
	v_pk_add_f32 v[92:93], v[90:91], 0 op_sel_hi:[1,0]
	v_cvt_pk_bf16_f32 v90, v98, v99
	v_cvt_pk_bf16_f32 v91, v96, v97
	v_pk_add_f32 v[62:63], v[62:63], 0 op_sel_hi:[1,0]
	v_cvt_pk_bf16_f32 v92, v92, v93
	v_cvt_pk_bf16_f32 v93, v100, v101
	ds_bpermute_b32 v208, v248, v90
	ds_bpermute_b32 v209, v248, v91
	ds_bpermute_b32 v210, v248, v92
	ds_bpermute_b32 v211, v248, v93
	v_mov_b32_e32 v224, v94
	v_mov_b32_e32 v225, v95
	s_waitcnt lgkmcnt(4)
	global_store_dwordx4 v[230:231], v[220:223], off offset:256
	v_pk_add_f32 v[64:65], v[64:65], 0 op_sel_hi:[1,0]
	v_pk_add_f32 v[56:57], v[56:57], 0 op_sel_hi:[1,0]
	v_pk_add_f32 v[90:91], v[80:81], 0 op_sel_hi:[1,0]
	v_pk_add_f32 v[80:81], v[78:79], 0 op_sel_hi:[1,0]
	v_cvt_pk_bf16_f32 v78, v86, v87
	v_cvt_pk_bf16_f32 v79, v88, v89
	v_pk_add_f32 v[54:55], v[54:55], 0 op_sel_hi:[1,0]
	v_cvt_pk_bf16_f32 v80, v80, v81
	v_cvt_pk_bf16_f32 v81, v90, v91
	ds_bpermute_b32 v212, v248, v78
	ds_bpermute_b32 v213, v248, v79
	ds_bpermute_b32 v214, v248, v80
	ds_bpermute_b32 v215, v248, v81
	v_mov_b32_e32 v226, v94
	v_mov_b32_e32 v227, v95
	s_waitcnt lgkmcnt(4)
	global_store_dwordx4 v[224:225], v[208:211], off
	v_pk_add_f32 v[50:51], v[50:51], 0 op_sel_hi:[1,0]
	v_pk_add_f32 v[40:41], v[40:41], 0 op_sel_hi:[1,0]
	v_or_b32_e32 v78, 48, v146
	v_ashrrev_i32_e32 v79, 31, v78
	v_lshlrev_b64 v[78:79], 11, v[78:79]
	v_lshl_add_u64 v[78:79], v[148:149], 0, v[78:79]
	v_pk_add_f32 v[80:81], v[84:85], 0 op_sel_hi:[1,0]
	v_pk_add_f32 v[84:85], v[76:77], 0 op_sel_hi:[1,0]
	v_pk_add_f32 v[76:77], v[74:75], 0 op_sel_hi:[1,0]
	v_cvt_pk_bf16_f32 v74, v82, v83
	v_cvt_pk_bf16_f32 v75, v80, v81
	v_pk_add_f32 v[38:39], v[38:39], 0 op_sel_hi:[1,0]
	v_cvt_pk_bf16_f32 v76, v76, v77
	v_cvt_pk_bf16_f32 v77, v84, v85
	ds_bpermute_b32 v216, v248, v74
	ds_bpermute_b32 v217, v248, v75
	ds_bpermute_b32 v218, v248, v76
	ds_bpermute_b32 v219, v248, v77
	v_mov_b32_e32 v228, v78
	v_mov_b32_e32 v229, v79
	s_waitcnt lgkmcnt(4)
; __device__ __forceinline__ unsigned cvt_pk_bf16(float lo, float hi) { unsigned r; asm volatile("v_cvt_pk_bf16_f32 %0, %1, %2" : "=v"(r) : "v"(lo), "v"(hi)); return r; }
;     __device__ __forceinline__ void operator()(const f32x4 (&acc)[2][2][4][2], const Unit& u, int wr, int wc, int fr, int fq) const {
;     ...
;         for (int ai = 0; ai < 2; ++ai)
; #pragma unroll
;             for (int m = 0; m < 4; ++m) { bf16_t* rowp = base + (size_t)(row0 + ai * HALF + m * 16) * ldc + col0;
; #pragma unroll
;                 for (int bj = 0; bj < 2; ++bj) { f32x4 v0 = acc[ai][bj][m][0] + bv[bj][0], v1 = acc[ai][bj][m][1] + bv[bj][1];
;                     if (ACT == 1) { f32x2 a = gelu_pk((f32x2){v0[0], v0[1]}), b = gelu_pk((f32x2){v0[2], v0[3]}), c = gelu_pk((f32x2){v1[0], v1[1]}), d = gelu_pk((f32x2){v1[2], v1[3]});
;                         v0 = (f32x4){a.x, a.y, b.x, b.y}; v1 = (f32x4){c.x, c.y, d.x, d.y}; }
;                     v0 = v0 * sc; v1 = v1 * sc; u32x4 w; w.x = cvt_pk_bf16(v0[0], v0[1]); w.y = cvt_pk_bf16(v0[2], v0[3]); w.z = cvt_pk_bf16(v1[0], v1[1]); w.w = cvt_pk_bf16(v1[2], v1[3]);
;                     *(u32x4*)(rowp + bj * HALF) = w; } }
;     ...
;         if constexpr (!Epi::AFTER_DRAIN) { E(acc, cur, wr, wc, fr, fq); S.done(cur); }
;         if (!has_next) break;
	global_store_dwordx4 v[226:227], v[212:215], off offset:256
	v_pk_add_f32 v[34:35], v[34:35], 0 op_sel_hi:[1,0]
	v_pk_add_f32 v[24:25], v[24:25], 0 op_sel_hi:[1,0]
	v_pk_add_f32 v[74:75], v[68:69], 0 op_sel_hi:[1,0]
	v_pk_add_f32 v[68:69], v[66:67], 0 op_sel_hi:[1,0]
	v_cvt_pk_bf16_f32 v66, v70, v71
	v_cvt_pk_bf16_f32 v67, v72, v73
	v_pk_add_f32 v[22:23], v[22:23], 0 op_sel_hi:[1,0]
	v_cvt_pk_bf16_f32 v68, v68, v69
	v_cvt_pk_bf16_f32 v69, v74, v75
	ds_bpermute_b32 v220, v248, v66
	ds_bpermute_b32 v221, v248, v67
	ds_bpermute_b32 v222, v248, v68
	ds_bpermute_b32 v223, v248, v69
	v_mov_b32_e32 v230, v78
	v_mov_b32_e32 v231, v79
	s_waitcnt lgkmcnt(4)
	global_store_dwordx4 v[228:229], v[216:219], off
	v_pk_add_f32 v[18:19], v[18:19], 0 op_sel_hi:[1,0]
	v_pk_add_f32 v[8:9], v[8:9], 0 op_sel_hi:[1,0]
	v_lshl_add_u64 v[66:67], v[140:141], 0, s[16:17]
	s_mov_b32 s16, 0x40000
	v_pk_add_f32 v[68:69], v[60:61], 0 op_sel_hi:[1,0]
	v_pk_add_f32 v[60:61], v[58:59], 0 op_sel_hi:[1,0]
	v_cvt_pk_bf16_f32 v58, v62, v63
	v_add_co_u32_e32 v62, vcc, s16, v140
	v_cvt_pk_bf16_f32 v59, v64, v65
	v_cvt_pk_bf16_f32 v60, v60, v61
	v_cvt_pk_bf16_f32 v61, v68, v69
	s_mov_b64 s[16:17], 0x48000
	s_nop 0
	v_addc_co_u32_e32 v63, vcc, 0, v141, vcc
	ds_bpermute_b32 v208, v248, v58
	ds_bpermute_b32 v209, v248, v59
	ds_bpermute_b32 v210, v248, v60
	ds_bpermute_b32 v211, v248, v61
	v_mov_b32_e32 v224, v62
	v_mov_b32_e32 v225, v63
	s_waitcnt lgkmcnt(4)
	global_store_dwordx4 v[230:231], v[220:223], off offset:256
	v_pk_add_f32 v[6:7], v[6:7], 0 op_sel_hi:[1,0]
	s_nop 0
	v_pk_add_f32 v[58:59], v[48:49], 0 op_sel_hi:[1,0]
	v_pk_add_f32 v[48:49], v[46:47], 0 op_sel_hi:[1,0]
	v_cvt_pk_bf16_f32 v46, v54, v55
	v_cvt_pk_bf16_f32 v47, v56, v57
	s_nop 0
	v_cvt_pk_bf16_f32 v48, v48, v49
	v_cvt_pk_bf16_f32 v49, v58, v59
	ds_bpermute_b32 v212, v248, v46
	ds_bpermute_b32 v213, v248, v47
	ds_bpermute_b32 v214, v248, v48
	ds_bpermute_b32 v215, v248, v49
	v_mov_b32_e32 v226, v66
	v_mov_b32_e32 v227, v67
	s_waitcnt lgkmcnt(4)
	global_store_dwordx4 v[224:225], v[208:211], off
	s_nop 1
	v_lshl_add_u64 v[46:47], v[140:141], 0, s[16:17]
	v_pk_add_f32 v[48:49], v[52:53], 0 op_sel_hi:[1,0]
	s_mov_b32 s16, 0x48000
	v_pk_add_f32 v[52:53], v[44:45], 0 op_sel_hi:[1,0]
	v_pk_add_f32 v[44:45], v[42:43], 0 op_sel_hi:[1,0]
	v_cvt_pk_bf16_f32 v42, v50, v51
	v_cvt_pk_bf16_f32 v43, v48, v49
	v_add_co_u32_e32 v48, vcc, s16, v140
	v_cvt_pk_bf16_f32 v44, v44, v45
	v_cvt_pk_bf16_f32 v45, v52, v53
	s_mov_b64 s[16:17], 0x50000
	s_nop 0
	v_addc_co_u32_e32 v49, vcc, 0, v141, vcc
	ds_bpermute_b32 v216, v248, v42
	ds_bpermute_b32 v217, v248, v43
	ds_bpermute_b32 v218, v248, v44
	ds_bpermute_b32 v219, v248, v45
	v_mov_b32_e32 v228, v48
	v_mov_b32_e32 v229, v49
	s_waitcnt lgkmcnt(4)
	global_store_dwordx4 v[226:227], v[212:215], off offset:256
	s_nop 1
	v_pk_add_f32 v[42:43], v[32:33], 0 op_sel_hi:[1,0]
	v_pk_add_f32 v[32:33], v[30:31], 0 op_sel_hi:[1,0]
	v_cvt_pk_bf16_f32 v30, v38, v39
	v_cvt_pk_bf16_f32 v31, v40, v41
	s_nop 0
	v_cvt_pk_bf16_f32 v32, v32, v33
	v_cvt_pk_bf16_f32 v33, v42, v43
	ds_bpermute_b32 v220, v248, v30
	ds_bpermute_b32 v221, v248, v31
	ds_bpermute_b32 v222, v248, v32
	ds_bpermute_b32 v223, v248, v33
	v_mov_b32_e32 v230, v46
	v_mov_b32_e32 v231, v47
	s_waitcnt lgkmcnt(4)
	global_store_dwordx4 v[228:229], v[216:219], off
	s_nop 1
	v_lshl_add_u64 v[30:31], v[140:141], 0, s[16:17]
	v_pk_add_f32 v[32:33], v[36:37], 0 op_sel_hi:[1,0]
	s_mov_b32 s16, 0x50000
	v_pk_add_f32 v[36:37], v[28:29], 0 op_sel_hi:[1,0]
	v_pk_add_f32 v[28:29], v[26:27], 0 op_sel_hi:[1,0]
	v_cvt_pk_bf16_f32 v26, v34, v35
	v_cvt_pk_bf16_f32 v27, v32, v33
	v_add_co_u32_e32 v32, vcc, s16, v140
	v_cvt_pk_bf16_f32 v28, v28, v29
	v_cvt_pk_bf16_f32 v29, v36, v37
	s_mov_b64 s[16:17], 0x58000
	s_nop 0
	v_addc_co_u32_e32 v33, vcc, 0, v141, vcc
	ds_bpermute_b32 v208, v248, v26
	ds_bpermute_b32 v209, v248, v27
	ds_bpermute_b32 v210, v248, v28
	ds_bpermute_b32 v211, v248, v29
	v_mov_b32_e32 v224, v32
	v_mov_b32_e32 v225, v33
	s_waitcnt lgkmcnt(4)
	global_store_dwordx4 v[230:231], v[220:223], off offset:256
	s_nop 1
	v_pk_add_f32 v[26:27], v[16:17], 0 op_sel_hi:[1,0]
	v_pk_add_f32 v[16:17], v[14:15], 0 op_sel_hi:[1,0]
	v_cvt_pk_bf16_f32 v14, v22, v23
	v_cvt_pk_bf16_f32 v15, v24, v25
	s_nop 0
	v_cvt_pk_bf16_f32 v16, v16, v17
	v_cvt_pk_bf16_f32 v17, v26, v27
	ds_bpermute_b32 v212, v248, v14
	ds_bpermute_b32 v213, v248, v15
	ds_bpermute_b32 v214, v248, v16
	ds_bpermute_b32 v215, v248, v17
	v_mov_b32_e32 v226, v30
	v_mov_b32_e32 v227, v31
	s_waitcnt lgkmcnt(4)
	global_store_dwordx4 v[224:225], v[208:211], off
	s_nop 1
	v_lshl_add_u64 v[14:15], v[140:141], 0, s[16:17]
	v_pk_add_f32 v[16:17], v[20:21], 0 op_sel_hi:[1,0]
	s_mov_b32 s16, 0x58000
	v_pk_add_f32 v[20:21], v[12:13], 0 op_sel_hi:[1,0]
	v_pk_add_f32 v[12:13], v[10:11], 0 op_sel_hi:[1,0]
	v_cvt_pk_bf16_f32 v10, v18, v19
	v_cvt_pk_bf16_f32 v11, v16, v17
	v_add_co_u32_e32 v16, vcc, s16, v140
	v_cvt_pk_bf16_f32 v12, v12, v13
	v_cvt_pk_bf16_f32 v13, v20, v21
	s_mov_b64 s[16:17], -1
	s_nop 0
	v_addc_co_u32_e32 v17, vcc, 0, v141, vcc
	ds_bpermute_b32 v216, v248, v10
	ds_bpermute_b32 v217, v248, v11
	ds_bpermute_b32 v218, v248, v12
	ds_bpermute_b32 v219, v248, v13
	v_mov_b32_e32 v228, v16
	v_mov_b32_e32 v229, v17
	s_waitcnt lgkmcnt(4)
	global_store_dwordx4 v[226:227], v[212:215], off offset:256
	s_and_b64 vcc, exec, s[36:37]
	s_nop 0
	v_pk_add_f32 v[10:11], v[4:5], 0 op_sel_hi:[1,0]
	v_pk_add_f32 v[4:5], v[2:3], 0 op_sel_hi:[1,0]
	v_cvt_pk_bf16_f32 v2, v6, v7
	v_cvt_pk_bf16_f32 v3, v8, v9
	s_nop 0
	v_cvt_pk_bf16_f32 v4, v4, v5
	v_cvt_pk_bf16_f32 v5, v10, v11
	ds_bpermute_b32 v220, v248, v2
	ds_bpermute_b32 v221, v248, v3
	ds_bpermute_b32 v222, v248, v4
	ds_bpermute_b32 v223, v248, v5
	v_mov_b32_e32 v230, v14
	v_mov_b32_e32 v231, v15
	s_waitcnt lgkmcnt(4)
	global_store_dwordx4 v[228:229], v[216:219], off
	s_waitcnt lgkmcnt(0)
	global_store_dwordx4 v[230:231], v[220:223], off offset:256
	s_cbranch_vccnz .LBB0_644
	s_andn2_b64 vcc, exec, s[40:41]
	s_cbranch_vccnz .LBB0_643
	s_barrier
	s_branch .LBB0_643
